# RG-LRU prompt tile loop: ssq lane reduction via DPP adds instead of three ds_bpermute round trips; conv-section LDS reads software-pipelined two groups deep
# baseline (speedup 1.0000x reference)
.LBB0_513:
	s_or_b64 exec, exec, s[26:27]
	s_waitcnt lgkmcnt(0)
	s_barrier
	ds_read_b128 v[12:15], v46
	s_waitcnt lgkmcnt(4)
	ds_read_b128 v[16:19], v46 offset:16
	ds_read_b128 v[20:23], v47
	ds_read_b128 v[24:27], v47 offset:16
	ds_read_b128 v[98:101], v43 offset:18432
	ds_read_b128 v[102:105], v43 offset:18448
	ds_read_b128 v[134:137], v47 offset:256
	ds_read_b128 v[138:141], v47 offset:272
	ds_read_b128 v[142:145], v43 offset:18688
	ds_read_b128 v[146:149], v43 offset:18704
	s_waitcnt lgkmcnt(5)
	v_pk_fma_f32 v[100:101], v[22:23], v[100:101], v[14:15]
	v_pk_fma_f32 v[98:99], v[20:21], v[98:99], v[12:13]
	s_waitcnt lgkmcnt(4)
	v_pk_fma_f32 v[104:105], v[26:27], v[104:105], v[18:19]
	v_pk_fma_f32 v[102:103], v[24:25], v[102:103], v[16:17]
	ds_read_b128 v[12:15], v47 offset:512
	ds_read_b128 v[16:19], v47 offset:528
	ds_read_b128 v[20:23], v43 offset:18944
	ds_read_b128 v[24:27], v43 offset:18960
	s_waitcnt lgkmcnt(5)
	v_pk_fma_f32 v[100:101], v[136:137], v[144:145], v[100:101]
	v_pk_fma_f32 v[98:99], v[134:135], v[142:143], v[98:99]
	s_waitcnt lgkmcnt(4)
	v_pk_fma_f32 v[104:105], v[140:141], v[148:149], v[104:105]
	v_pk_fma_f32 v[102:103], v[138:139], v[146:147], v[102:103]
	ds_read_b128 v[134:137], v47 offset:768
	ds_read_b128 v[138:141], v47 offset:784
	ds_read_b128 v[142:145], v43 offset:19200
	ds_read_b128 v[146:149], v43 offset:19216
	s_waitcnt lgkmcnt(5)
	v_pk_fma_f32 v[100:101], v[14:15], v[22:23], v[100:101]
	v_pk_fma_f32 v[98:99], v[12:13], v[20:21], v[98:99]
	s_waitcnt lgkmcnt(4)
	v_pk_fma_f32 v[104:105], v[18:19], v[26:27], v[104:105]
	v_pk_fma_f32 v[102:103], v[16:17], v[24:25], v[102:103]
	s_waitcnt lgkmcnt(1)
	v_pk_fma_f32 v[14:15], v[136:137], v[144:145], v[100:101]
	v_pk_fma_f32 v[12:13], v[134:135], v[142:143], v[98:99]
	s_waitcnt lgkmcnt(0)
	v_pk_fma_f32 v[18:19], v[140:141], v[148:149], v[104:105]
	v_pk_fma_f32 v[16:17], v[138:139], v[146:147], v[102:103]
	ds_write_b128 v96, v[12:15] offset:35584
	ds_write_b128 v96, v[16:19] offset:35600
	v_cvt_pk_bf16_f32 v12, v12, v13
	v_cvt_pk_bf16_f32 v13, v14, v15
	v_cvt_pk_bf16_f32 v14, v16, v17
	v_cvt_pk_bf16_f32 v15, v18, v19
	ds_write_b128 v92, v[12:15] offset:53248
	s_waitcnt lgkmcnt(0)
	s_barrier
	ds_read_b32 v125, v3 offset:35584
	ds_read_b32 v126, v3 offset:35856
	ds_read_b32 v127, v3 offset:36128
	ds_read_b32 v128, v3 offset:36400
	ds_read_b32 v129, v3 offset:35648
	ds_read_b32 v130, v56 offset:35856
	ds_read_b32 v131, v56 offset:36128
	ds_read_b32 v132, v56 offset:36400
	ds_read_b128 v[16:19], v93 offset:53248
	ds_read_b128 v[12:15], v93 offset:53312
	ds_read_b128 v[20:23], v2
	ds_read_b128 v[24:27], v2 offset:9216
	s_waitcnt lgkmcnt(1)
	v_mfma_f32_16x16x32_bf16 v[20:23], v[16:19], v[20:23], 0
	s_waitcnt lgkmcnt(0)
	v_mfma_f32_16x16x32_bf16 v[98:101], v[16:19], v[24:27], 0
	ds_read_b128 v[24:27], v2 offset:64
	ds_read_b128 v[102:105], v2 offset:9280
	s_waitcnt lgkmcnt(1)
	v_mfma_f32_16x16x32_bf16 v[24:27], v[12:15], v[24:27], v[20:23]
	s_waitcnt lgkmcnt(0)
	v_mfma_f32_16x16x32_bf16 v[20:23], v[12:15], v[102:105], v[98:101]
	s_waitcnt vmcnt(3)
	s_nop 4
	v_add_f32_e32 v24, v1, v24
	v_mul_f32_e32 v24, 0xbfb8aa3b, v24
	v_exp_f32_e32 v24, v24
	s_nop 0
	v_add_f32_e32 v24, 1.0, v24
	v_rcp_f32_e32 v24, v24
	s_waitcnt vmcnt(1)
	v_add_f32_e32 v20, v38, v20
	v_mul_f32_e32 v20, 0xbfb8aa3b, v20
	v_exp_f32_e32 v20, v20
	v_mul_f32_e32 v24, v41, v24
	v_exp_f32_e32 v24, v24
	v_add_f32_e32 v21, v38, v21
	v_add_f32_e32 v20, 1.0, v20
	v_rcp_f32_e32 v20, v20
	v_fma_f32 v97, -v24, v24, 1.0
	v_max_f32_e32 v97, 0, v97
	v_sqrt_f32_e32 v97, v97
	ds_write_b32 v3, v24 offset:62464
	v_mul_f32_e32 v21, 0xbfb8aa3b, v21
	v_mul_f32_e32 v20, v20, v97
	v_exp_f32_e32 v21, v21
	v_mul_f32_e32 v20, v125, v20
	ds_write_b32 v52, v20
	v_add_f32_e32 v20, v1, v25
	v_mul_f32_e32 v20, 0xbfb8aa3b, v20
	v_exp_f32_e32 v20, v20
	v_add_f32_e32 v21, 1.0, v21
	v_rcp_f32_e32 v21, v21
	v_add_f32_e32 v20, 1.0, v20
	v_rcp_f32_e32 v20, v20
	s_nop 0
	v_mul_f32_e32 v20, v41, v20
	v_exp_f32_e32 v20, v20
	ds_write_b32 v3, v20 offset:62736
	v_fma_f32 v24, -v20, v20, 1.0
	v_max_f32_e32 v24, 0, v24
	v_sqrt_f32_e32 v24, v24
	s_nop 0
	v_mul_f32_e32 v20, v21, v24
	v_mul_f32_e32 v20, v126, v20
	ds_write_b32 v53, v20
	v_add_f32_e32 v20, v1, v26
	v_mul_f32_e32 v20, 0xbfb8aa3b, v20
	v_exp_f32_e32 v20, v20
	v_add_f32_e32 v21, v38, v22
	v_mul_f32_e32 v21, 0xbfb8aa3b, v21
	v_exp_f32_e32 v21, v21
	v_add_f32_e32 v20, 1.0, v20
	v_rcp_f32_e32 v20, v20
	v_add_f32_e32 v21, 1.0, v21
	v_rcp_f32_e32 v21, v21
	v_mul_f32_e32 v20, v41, v20
	v_exp_f32_e32 v20, v20
	ds_write_b32 v3, v20 offset:63008
	v_fma_f32 v22, -v20, v20, 1.0
	v_max_f32_e32 v22, 0, v22
	v_sqrt_f32_e32 v22, v22
	s_nop 0
	v_mul_f32_e32 v20, v21, v22
	v_mul_f32_e32 v20, v127, v20
	ds_write_b32 v54, v20
	v_add_f32_e32 v20, v1, v27
	v_mul_f32_e32 v20, 0xbfb8aa3b, v20
	v_exp_f32_e32 v20, v20
	v_add_f32_e32 v21, v38, v23
	v_mul_f32_e32 v21, 0xbfb8aa3b, v21
	v_exp_f32_e32 v21, v21
	v_add_f32_e32 v20, 1.0, v20
	v_rcp_f32_e32 v20, v20
	v_add_f32_e32 v21, 1.0, v21
	v_rcp_f32_e32 v21, v21
	v_mul_f32_e32 v20, v41, v20
	v_exp_f32_e32 v20, v20
	ds_write_b32 v3, v20 offset:63280
	v_fma_f32 v22, -v20, v20, 1.0
	v_max_f32_e32 v22, 0, v22
	v_sqrt_f32_e32 v22, v22
	s_nop 0
	v_mul_f32_e32 v20, v21, v22
	v_mul_f32_e32 v20, v128, v20
	ds_write_b32 v55, v20
	ds_read_b128 v[20:23], v30
	ds_read_b128 v[24:27], v30 offset:9216
	s_waitcnt lgkmcnt(1)
	v_mfma_f32_16x16x32_bf16 v[20:23], v[16:19], v[20:23], 0
	s_waitcnt lgkmcnt(0)
	v_mfma_f32_16x16x32_bf16 v[16:19], v[16:19], v[24:27], 0
	ds_read_b128 v[24:27], v30 offset:64
	ds_read_b128 v[98:101], v30 offset:9280
	s_waitcnt lgkmcnt(1)
	v_mfma_f32_16x16x32_bf16 v[20:23], v[12:15], v[24:27], v[20:23]
	s_waitcnt lgkmcnt(0)
	v_mfma_f32_16x16x32_bf16 v[12:15], v[12:15], v[98:101], v[16:19]
	s_nop 5
	v_add_f32_e32 v16, v29, v20
	v_mul_f32_e32 v16, 0xbfb8aa3b, v16
	v_exp_f32_e32 v16, v16
	s_waitcnt vmcnt(0)
	v_add_f32_e32 v12, v39, v12
	v_mul_f32_e32 v12, 0xbfb8aa3b, v12
	v_exp_f32_e32 v12, v12
	v_add_f32_e32 v16, 1.0, v16
	v_rcp_f32_e32 v16, v16
	v_add_f32_e32 v13, v39, v13
	v_add_f32_e32 v12, 1.0, v12
	v_rcp_f32_e32 v12, v12
	v_mul_f32_e32 v16, v42, v16
	v_exp_f32_e32 v16, v16
	v_mul_f32_e32 v13, 0xbfb8aa3b, v13
	v_exp_f32_e32 v13, v13
	v_fma_f32 v17, -v16, v16, 1.0
	v_max_f32_e32 v17, 0, v17
	v_sqrt_f32_e32 v17, v17
	ds_write_b32 v3, v16 offset:62528
	v_add_f32_e32 v13, 1.0, v13
	v_mul_f32_e32 v12, v12, v17
	v_rcp_f32_e32 v13, v13
	v_mul_f32_e32 v12, v129, v12
	ds_write_b32 v31, v12
	v_add_f32_e32 v12, v29, v21
	v_mul_f32_e32 v12, 0xbfb8aa3b, v12
	v_exp_f32_e32 v12, v12
	s_nop 0
	v_add_f32_e32 v12, 1.0, v12
	v_rcp_f32_e32 v12, v12
	s_nop 0
	v_mul_f32_e32 v12, v42, v12
	v_exp_f32_e32 v12, v12
	ds_write_b32 v56, v12 offset:62736
	v_fma_f32 v16, -v12, v12, 1.0
	v_max_f32_e32 v16, 0, v16
	v_sqrt_f32_e32 v16, v16
	s_nop 0
	v_mul_f32_e32 v12, v13, v16
	v_mul_f32_e32 v12, v130, v12
	ds_write_b32 v57, v12
	v_add_f32_e32 v12, v29, v22
	v_mul_f32_e32 v12, 0xbfb8aa3b, v12
	v_exp_f32_e32 v12, v12
	v_add_f32_e32 v13, v39, v14
	v_mul_f32_e32 v13, 0xbfb8aa3b, v13
	v_exp_f32_e32 v13, v13
	v_add_f32_e32 v12, 1.0, v12
	v_rcp_f32_e32 v12, v12
	v_add_f32_e32 v13, 1.0, v13
	v_rcp_f32_e32 v13, v13
	v_mul_f32_e32 v12, v42, v12
	v_exp_f32_e32 v12, v12
	ds_write_b32 v56, v12 offset:63008
	v_fma_f32 v14, -v12, v12, 1.0
	v_max_f32_e32 v14, 0, v14
	v_sqrt_f32_e32 v14, v14
	s_nop 0
	v_mul_f32_e32 v12, v13, v14
	v_mul_f32_e32 v12, v131, v12
	ds_write_b32 v58, v12
	v_add_f32_e32 v12, v29, v23
	v_mul_f32_e32 v12, 0xbfb8aa3b, v12
	v_exp_f32_e32 v12, v12
	v_add_f32_e32 v13, v39, v15
	v_mul_f32_e32 v13, 0xbfb8aa3b, v13
	v_exp_f32_e32 v13, v13
	v_add_f32_e32 v12, 1.0, v12
	v_rcp_f32_e32 v12, v12
	v_add_f32_e32 v13, 1.0, v13
	v_rcp_f32_e32 v13, v13
	v_mul_f32_e32 v12, v42, v12
	v_exp_f32_e32 v12, v12
	ds_write_b32 v56, v12 offset:63280
	v_fma_f32 v14, -v12, v12, 1.0
	v_max_f32_e32 v14, 0, v14
	v_sqrt_f32_e32 v14, v14
	s_nop 0
	v_mul_f32_e32 v12, v13, v14
	v_mul_f32_e32 v12, v132, v12
	ds_write_b32 v59, v12
	v_mov_b32_e32 v12, 0
	s_and_saveexec_b64 s[26:27], s[2:3]
	ds_read_b32 v12, v48 offset:34816
	s_or_b64 exec, exec, s[26:27]
	s_waitcnt lgkmcnt(0)
	s_barrier
	s_and_saveexec_b64 s[26:27], s[2:3]
	s_cbranch_execz .LBB0_517
	s_waitcnt lgkmcnt(0)
	ds_write_b32 v49, v12 offset:18432
.LBB0_517:
	s_or_b64 exec, exec, s[26:27]
	s_waitcnt lgkmcnt(0)
	ds_read_b32 v12, v60 offset:62464
	ds_read_b32 v13, v61
	ds_read_b32 v14, v62 offset:62464
	ds_read_b32 v15, v63
	ds_read_b32 v16, v64 offset:62464
	ds_read_b32 v17, v65
	ds_read_b32 v18, v66 offset:62464
	ds_read_b32 v19, v67
	ds_read_b32 v20, v68 offset:62464
	ds_read_b32 v22, v69
	ds_read_b32 v106, v70 offset:62464
	ds_read_b32 v24, v71
	ds_read_b32 v107, v72 offset:62464
	ds_read_b32 v26, v73
	s_waitcnt lgkmcnt(12)
	v_fmac_f32_e32 v13, 0, v12
	ds_read_b32 v108, v74 offset:62464
	ds_read_b32 v97, v75
	s_waitcnt lgkmcnt(12)
	v_fmac_f32_e32 v15, v13, v14
	v_mul_f32_e32 v14, v12, v14
	s_waitcnt lgkmcnt(10)
	v_fmac_f32_e32 v17, v15, v16
	v_mul_f32_e32 v16, v14, v16
	s_waitcnt lgkmcnt(8)
	v_fmac_f32_e32 v19, v17, v18
	v_mul_f32_e32 v18, v16, v18
	s_waitcnt lgkmcnt(6)
	v_fmac_f32_e32 v22, v19, v20
	v_mul_f32_e32 v23, v18, v20
	s_waitcnt lgkmcnt(4)
	v_mul_f32_e32 v25, v23, v106
	v_fmac_f32_e32 v24, v22, v106
	s_waitcnt lgkmcnt(2)
	v_mul_f32_e32 v27, v25, v107
	v_fmac_f32_e32 v26, v24, v107
	s_waitcnt lgkmcnt(0)
	v_mul_f32_e32 v98, v27, v108
	v_fmac_f32_e32 v97, v26, v108
	ds_write_b32 v50, v98
	ds_write_b32 v51, v97
	s_waitcnt lgkmcnt(0)
	s_barrier
	ds_read_b32 v109, v76
	ds_read_b32 v110, v77
	ds_read_b32 v111, v78
	ds_read_b32 v112, v79
	ds_read_b32 v113, v80
	ds_read_b32 v114, v81
	ds_read_b32 v115, v82
	ds_read_b32 v116, v83
	ds_read_b32 v117, v84
	ds_read_b32 v118, v85
	ds_read_b32 v119, v86
	ds_read_b32 v120, v87
	ds_read_b32 v121, v88
	ds_read_b32 v122, v89
	v_cndmask_b32_e64 v20, 0, v40, s[6:7]
	s_waitcnt lgkmcnt(12)
	v_fmac_f32_e32 v110, v40, v109
	ds_read_b32 v21, v90
	ds_read_b32 v40, v91
	v_cndmask_b32_e64 v20, v20, v110, s[8:9]
	s_waitcnt lgkmcnt(12)
	v_fmac_f32_e32 v112, v110, v111
	v_cndmask_b32_e64 v20, v20, v112, s[10:11]
	s_waitcnt lgkmcnt(10)
	v_fmac_f32_e32 v114, v112, v113
	v_cndmask_b32_e64 v20, v20, v114, s[12:13]
	s_waitcnt lgkmcnt(8)
	v_fmac_f32_e32 v116, v114, v115
	v_cndmask_b32_e64 v20, v20, v116, s[14:15]
	s_waitcnt lgkmcnt(6)
	v_fmac_f32_e32 v118, v116, v117
	v_cndmask_b32_e64 v20, v20, v118, s[16:17]
	s_waitcnt lgkmcnt(4)
	v_fmac_f32_e32 v120, v118, v119
	v_cndmask_b32_e64 v124, v20, v120, s[18:19]
	s_waitcnt lgkmcnt(2)
	v_fmac_f32_e32 v122, v120, v121
	v_mov_b32_e32 v20, v122
	v_cndmask_b32_e64 v99, v124, v122, s[20:21]
	v_fmac_f32_e32 v13, v12, v99
	v_fmac_f32_e32 v15, v14, v99
	v_fmac_f32_e32 v17, v16, v99
	v_add_u32_e32 v12, 0x8a00, v95
	ds_write2_b32 v12, v15, v17 offset0:64 offset1:132
	v_fmac_f32_e32 v19, v18, v99
	v_fmac_f32_e32 v22, v23, v99
	v_add_u32_e32 v12, 0x8c00, v95
	ds_write2_b32 v12, v19, v22 offset0:72 offset1:140
	v_fmac_f32_e32 v24, v25, v99
	v_fmac_f32_e32 v26, v27, v99
	v_add_u32_e32 v12, 0x8e00, v95
	v_fmac_f32_e32 v97, v98, v99
	ds_write_b32 v94, v13 offset:35584
	ds_write2_b32 v12, v24, v26 offset0:80 offset1:148
	ds_write_b32 v95, v97 offset:37216
	s_waitcnt lgkmcnt(0)
	s_barrier
	ds_read_b128 v[22:25], v96 offset:35584
	ds_read_b128 v[12:15], v96 offset:35600
	ds_read_b128 v[16:19], v44
	s_waitcnt lgkmcnt(0)
	v_lshlrev_b32_e32 v26, 16, v16
	v_mul_f32_e32 v27, 0x3d372713, v26
	v_mul_f32_e32 v27, v27, v26
	v_fma_f32 v27, v27, v26, v26
	v_mul_f32_e32 v27, 0x3f4c422a, v27
	v_mul_f32_e32 v27, 0x4038aa3b, v27
	v_exp_f32_e32 v27, v27
	v_mul_f32_e32 v26, 0.5, v26
	v_and_b32_e32 v16, 0xffff0000, v16
	v_add_f32_e32 v27, 1.0, v27
	v_rcp_f32_e32 v27, v27
	s_nop 0
	v_fma_f32 v27, v27, -2.0, 1.0
	v_add_f32_e32 v27, 1.0, v27
	v_mul_f32_e32 v26, v26, v27
	v_mul_f32_e32 v22, v22, v26
	v_mul_f32_e32 v26, 0x3d372713, v16
	v_mul_f32_e32 v26, v26, v16
	v_fma_f32 v26, v26, v16, v16
	v_mul_f32_e32 v26, 0x3f4c422a, v26
	v_mul_f32_e32 v26, 0x4038aa3b, v26
	v_exp_f32_e32 v26, v26
	v_mul_f32_e32 v16, 0.5, v16
	v_add_f32_e32 v26, 1.0, v26
	v_rcp_f32_e32 v26, v26
	s_nop 0
	v_fma_f32 v26, v26, -2.0, 1.0
	v_add_f32_e32 v26, 1.0, v26
	v_mul_f32_e32 v16, v16, v26
	v_mul_f32_e32 v16, v23, v16
	v_lshlrev_b32_e32 v23, 16, v17
	v_mul_f32_e32 v26, 0x3d372713, v23
	v_mul_f32_e32 v26, v26, v23
	v_fma_f32 v26, v26, v23, v23
	v_mul_f32_e32 v26, 0x3f4c422a, v26
	v_mul_f32_e32 v26, 0x4038aa3b, v26
	v_exp_f32_e32 v26, v26
	v_mul_f32_e32 v23, 0.5, v23
	v_and_b32_e32 v17, 0xffff0000, v17
	v_add_f32_e32 v26, 1.0, v26
	v_rcp_f32_e32 v26, v26
	s_nop 0
	v_fma_f32 v26, v26, -2.0, 1.0
	v_add_f32_e32 v26, 1.0, v26
	v_mul_f32_e32 v23, v23, v26
	v_mul_f32_e32 v23, v24, v23
	v_mul_f32_e32 v24, 0x3d372713, v17
	v_mul_f32_e32 v24, v24, v17
	v_fma_f32 v24, v24, v17, v17
	v_mul_f32_e32 v24, 0x3f4c422a, v24
	v_mul_f32_e32 v24, 0x4038aa3b, v24
	v_exp_f32_e32 v24, v24
	v_mul_f32_e32 v17, 0.5, v17
	v_add_f32_e32 v24, 1.0, v24
	v_rcp_f32_e32 v24, v24
	s_nop 0
	v_fma_f32 v24, v24, -2.0, 1.0
	v_add_f32_e32 v24, 1.0, v24
	v_mul_f32_e32 v17, v17, v24
	v_lshlrev_b32_e32 v24, 16, v18
	v_mul_f32_e32 v17, v25, v17
	v_mul_f32_e32 v25, 0x3d372713, v24
	v_mul_f32_e32 v25, v25, v24
	v_fma_f32 v25, v25, v24, v24
	v_mul_f32_e32 v25, 0x3f4c422a, v25
	v_mul_f32_e32 v25, 0x4038aa3b, v25
	v_exp_f32_e32 v25, v25
	v_mul_f32_e32 v24, 0.5, v24
	v_and_b32_e32 v18, 0xffff0000, v18
	v_add_f32_e32 v25, 1.0, v25
	v_rcp_f32_e32 v25, v25
	s_nop 0
	v_fma_f32 v25, v25, -2.0, 1.0
	v_add_f32_e32 v25, 1.0, v25
	v_mul_f32_e32 v24, v24, v25
	v_mul_f32_e32 v12, v12, v24
	v_mul_f32_e32 v24, 0x3d372713, v18
	v_mul_f32_e32 v24, v24, v18
	v_fma_f32 v24, v24, v18, v18
	v_mul_f32_e32 v24, 0x3f4c422a, v24
	v_mul_f32_e32 v24, 0x4038aa3b, v24
	v_exp_f32_e32 v24, v24
	v_mul_f32_e32 v18, 0.5, v18
	v_add_f32_e32 v24, 1.0, v24
	v_rcp_f32_e32 v24, v24
	s_nop 0
	v_fma_f32 v24, v24, -2.0, 1.0
	v_add_f32_e32 v24, 1.0, v24
	v_mul_f32_e32 v18, v18, v24
	v_mul_f32_e32 v13, v13, v18
	v_lshlrev_b32_e32 v18, 16, v19
	v_mul_f32_e32 v24, 0x3d372713, v18
	v_mul_f32_e32 v24, v24, v18
	v_fma_f32 v24, v24, v18, v18
	v_mul_f32_e32 v24, 0x3f4c422a, v24
	v_mul_f32_e32 v24, 0x4038aa3b, v24
	v_exp_f32_e32 v24, v24
	v_mul_f32_e32 v18, 0.5, v18
	v_add_f32_e32 v24, 1.0, v24
	v_rcp_f32_e32 v24, v24
	s_nop 0
	v_fma_f32 v24, v24, -2.0, 1.0
	v_add_f32_e32 v24, 1.0, v24
	v_mul_f32_e32 v18, v18, v24
	v_mul_f32_e32 v14, v14, v18
	v_and_b32_e32 v18, 0xffff0000, v19
	v_mul_f32_e32 v19, 0x3d372713, v18
	v_mul_f32_e32 v19, v19, v18
	v_fma_f32 v19, v19, v18, v18
	v_mul_f32_e32 v19, 0x3f4c422a, v19
	v_mul_f32_e32 v19, 0x4038aa3b, v19
	v_exp_f32_e32 v19, v19
	v_mul_f32_e32 v18, 0.5, v18
	v_and_b32_e32 v24, 64, v190
	v_add_u32_e32 v24, 64, v24
	v_add_f32_e32 v19, 1.0, v19
	v_rcp_f32_e32 v19, v19
	s_nop 0
	v_fma_f32 v19, v19, -2.0, 1.0
	v_add_f32_e32 v19, 1.0, v19
	v_mul_f32_e32 v18, v18, v19
	v_mul_f32_e32 v15, v15, v18
	v_mul_f32_e32 v18, v16, v16
	v_mul_f32_e32 v19, v17, v17
	v_fmac_f32_e32 v18, v22, v22
	v_fmac_f32_e32 v19, v23, v23
	v_add_f32_e32 v18, v18, v19
	v_mul_f32_e32 v19, v13, v13
	v_fmac_f32_e32 v19, v12, v12
	v_add_f32_e32 v18, v19, v18
	v_mul_f32_e32 v19, v15, v15
	v_fmac_f32_e32 v19, v14, v14
	v_add_f32_e32 v18, v19, v18
	s_nop 1
	v_add_f32_dpp v18, v18, v18 quad_perm:[1,0,3,2] row_mask:0xf bank_mask:0xf
	s_nop 1
	v_add_f32_dpp v18, v18, v18 quad_perm:[2,3,0,1] row_mask:0xf bank_mask:0xf
	s_nop 1
	v_mov_b32_dpp v19, v18 row_half_mirror row_mask:0xf bank_mask:0xf
	s_and_saveexec_b64 vcc, s[22:23]
	s_cbranch_execz .LBB0_510
	v_cvt_pk_bf16_f32 v22, v22, v16
	v_cvt_pk_bf16_f32 v23, v23, v17
	v_cvt_pk_bf16_f32 v24, v12, v13
	v_lshl_add_u64 v[12:13], s[30:31], 0, v[36:37]
	v_cvt_pk_bf16_f32 v25, v14, v15
	global_store_dwordx4 v[12:13], v[22:25], off
	s_and_b64 exec, exec, s[4:5]
	s_cbranch_execz .LBB0_510
	s_waitcnt lgkmcnt(0)
	v_add_f32_e32 v14, v18, v19
	v_lshl_add_u64 v[12:13], s[30:31], 0, v[34:35]
	global_store_dword v[12:13], v14, off
	s_branch .LBB0_510
